# 256x256 GEMM tile write-out stores (P1, P5, P7b, P11) marked nt so fewer dirty lines remain for the barrier's L2 write-back
# speedup vs baseline: 1.0037x; 1.0037x over previous
; template <class Epi>
; DEV void gemm256_tile(const bf16_t* __restrict__ A, int lda, const bf16_t* __restrict__ Bt, int ldb, int K, unsigned char* lds, const Epi& epi) {
;     ...
; #pragma unroll 4
;         for (int i = 0; i < 16; ++i) {
;             const int idx = tid + 512 * i, row = idx >> 5, cp = idx & 31, c = cp ^ (row & 31);
;             const uint4 d = *(const uint4*)(lds + row * 512 + (cp << 4));
;             *(uint4*)(epi.obase + (size_t)row * epi.old + c * 8) = epi.finish(row, c * 8, d);
;         }
;         __syncthreads();
.LBB0_176:
	v_add_u32_e32 v3, s19, v150
	v_ashrrev_i32_e32 v4, 5, v3
	v_add_u32_e32 v5, 0x200, v3
	v_add_u32_e32 v6, 0x400, v3
	v_add_u32_e32 v3, 0x600, v3
	v_xor_b32_e32 v7, v4, v150
	v_lshl_or_b32 v8, v4, 9, v2
	v_ashrrev_i32_e32 v9, 5, v5
	v_ashrrev_i32_e32 v10, 5, v6
	v_ashrrev_i32_e32 v3, 5, v3
	v_mad_i64_i32 v[20:21], s[20:21], v4, s17, v[26:27]
	v_lshlrev_b32_e32 v11, 4, v7
	ds_read_b128 v[4:7], v8
	v_xor_b32_e32 v8, v9, v150
	v_lshl_or_b32 v12, v9, 9, v2
	v_xor_b32_e32 v13, v10, v150
	v_lshl_or_b32 v14, v10, 9, v2
	v_xor_b32_e32 v15, v3, v150
	v_lshl_or_b32 v16, v3, 9, v2
	v_mad_i64_i32 v[22:23], s[20:21], v9, s17, v[26:27]
	v_mad_i64_i32 v[24:25], s[20:21], v10, s17, v[26:27]
	v_mad_i64_i32 v[28:29], s[20:21], v3, s17, v[26:27]
	v_and_b32_e32 v142, 0x1f0, v11
	v_lshlrev_b32_e32 v3, 4, v8
	ds_read_b128 v[8:11], v12
	v_lshlrev_b32_e32 v30, 4, v13
	v_lshlrev_b32_e32 v31, 4, v15
	ds_read_b128 v[12:15], v14
	ds_read_b128 v[16:19], v16
	v_lshl_add_u64 v[20:21], v[20:21], 0, v[142:143]
	v_and_b32_e32 v142, 0x1f0, v3
	s_addk_i32 s19, 0x800
	v_lshl_add_u64 v[22:23], v[22:23], 0, v[142:143]
	v_and_b32_e32 v142, 0x1f0, v30
	s_cmpk_lg_i32 s19, 0x2000
	v_lshl_add_u64 v[24:25], v[24:25], 0, v[142:143]
	v_and_b32_e32 v142, 0x1f0, v31
	s_waitcnt lgkmcnt(3)
	global_store_dwordx4 v[20:21], v[4:7], off nt
	s_nop 1
	v_lshl_add_u64 v[4:5], v[28:29], 0, v[142:143]
	s_waitcnt lgkmcnt(2)
	global_store_dwordx4 v[22:23], v[8:11], off nt
	s_waitcnt lgkmcnt(1)
	global_store_dwordx4 v[24:25], v[12:15], off nt
	s_waitcnt lgkmcnt(0)
	global_store_dwordx4 v[4:5], v[16:19], off nt
	s_cbranch_scc1 .LBB0_176
	s_add_i32 s18, s18, s33
	s_cmpk_gt_i32 s18, 0x2ff
	s_barrier
	s_cbranch_scc0 .LBB0_173

; template <class Epi>
; DEV void gemm256_tile(const bf16_t* __restrict__ A, int lda, const bf16_t* __restrict__ Bt, int ldb, int K, unsigned char* lds, const Epi& epi) {
;     ...
; #pragma unroll 4
;         for (int i = 0; i < 16; ++i) {
;             const int idx = tid + 512 * i, row = idx >> 5, cp = idx & 31, c = cp ^ (row & 31);
;             const uint4 d = *(const uint4*)(lds + row * 512 + (cp << 4));
;             *(uint4*)(epi.obase + (size_t)row * epi.old + c * 8) = epi.finish(row, c * 8, d);
;         }
;     DEV uint4 finish(int r, int c, uint4 d) const {
;         const f32x4 a = __builtin_nontemporal_load((const f32x4*)(res + (size_t)r * D + c)), b = __builtin_nontemporal_load((const f32x4*)(res + (size_t)r * D + c + 4));
;         const float r8[8] = {a[0], a[1], a[2], a[3], b[0], b[1], b[2], b[3]};
;         return add8_bf16(d, r8);
;     }
.LBB0_1005:
	v_add_u32_e32 v3, s18, v142
	v_ashrrev_i32_e32 v12, 5, v3
	v_xor_b32_e32 v4, v12, v142
	v_ashrrev_i32_e32 v13, 31, v12
	v_lshlrev_b32_e32 v6, 3, v4
	v_lshlrev_b64 v[4:5], 13, v[12:13]
	v_and_b32_e32 v22, 0xf8, v6
	v_lshl_add_u64 v[4:5], s[16:17], 0, v[4:5]
	v_lshlrev_b32_e32 v136, 2, v22
	v_lshl_add_u64 v[14:15], v[4:5], 0, v[136:137]
	global_load_dwordx4 v[4:7], v[14:15], off nt
	global_load_dwordx4 v[8:11], v[14:15], off offset:16 nt
	v_add_u32_e32 v13, 0x200, v3
	v_lshl_or_b32 v14, v12, 9, v2
	v_mad_i64_i32 v[16:17], s[24:25], v12, s21, v[26:27]
	v_ashrrev_i32_e32 v18, 5, v13
	ds_read_b128 v[12:15], v14
	v_xor_b32_e32 v20, v18, v142
	v_lshlrev_b32_e32 v23, 3, v20
	v_ashrrev_i32_e32 v19, 31, v18
	v_and_b32_e32 v28, 0xf8, v23
	v_lshlrev_b32_e32 v136, 1, v22
	s_waitcnt lgkmcnt(0)
	v_lshlrev_b32_e32 v22, 16, v12
	v_and_b32_e32 v23, 0xffff0000, v12
	v_lshlrev_b32_e32 v12, 16, v13
	v_and_b32_e32 v13, 0xffff0000, v13
	v_lshlrev_b32_e32 v24, 16, v14
	v_and_b32_e32 v25, 0xffff0000, v14
	v_lshlrev_b32_e32 v14, 16, v15
	v_and_b32_e32 v15, 0xffff0000, v15
	v_lshlrev_b64 v[20:21], 13, v[18:19]
	v_lshl_add_u64 v[20:21], s[16:17], 0, v[20:21]
	v_lshl_add_u64 v[16:17], v[16:17], 0, v[136:137]
	v_lshlrev_b32_e32 v136, 2, v28
	v_lshl_add_u64 v[20:21], v[20:21], 0, v[136:137]
	v_lshlrev_b32_e32 v136, 1, v28
	s_addk_i32 s18, 0x800
	s_cmpk_lg_i32 s18, 0x2000
	s_waitcnt vmcnt(1)
	v_pk_add_f32 v[4:5], v[4:5], v[22:23]
	v_pk_add_f32 v[6:7], v[6:7], v[12:13]
	s_waitcnt vmcnt(0)
	v_pk_add_f32 v[8:9], v[8:9], v[24:25]
	v_pk_add_f32 v[10:11], v[10:11], v[14:15]
	v_cvt_pk_bf16_f32 v4, v4, v5
	v_cvt_pk_bf16_f32 v5, v6, v7
	v_cvt_pk_bf16_f32 v6, v8, v9
	v_cvt_pk_bf16_f32 v7, v10, v11
	global_store_dwordx4 v[16:17], v[4:7], off nt
	global_load_dwordx4 v[4:7], v[20:21], off nt
	s_nop 0
	global_load_dwordx4 v[8:11], v[20:21], off offset:16 nt
	v_add_u32_e32 v12, 0x400, v3
	v_ashrrev_i32_e32 v16, 5, v12
	v_lshl_or_b32 v12, v18, 9, v2
	ds_read_b128 v[12:15], v12
	v_xor_b32_e32 v20, v16, v142
	v_lshlrev_b32_e32 v22, 3, v20
	v_ashrrev_i32_e32 v17, 31, v16
	v_and_b32_e32 v29, 0xf8, v22
	s_waitcnt lgkmcnt(0)
	v_lshlrev_b32_e32 v22, 16, v12
	v_and_b32_e32 v23, 0xffff0000, v12
	v_lshlrev_b32_e32 v12, 16, v13
	v_and_b32_e32 v13, 0xffff0000, v13
	v_lshlrev_b32_e32 v24, 16, v14
	v_and_b32_e32 v25, 0xffff0000, v14
	v_lshlrev_b32_e32 v14, 16, v15
	v_and_b32_e32 v15, 0xffff0000, v15
	v_mad_i64_i32 v[18:19], s[24:25], v18, s21, v[26:27]
	v_lshlrev_b64 v[20:21], 13, v[16:17]
	v_lshl_add_u64 v[20:21], s[16:17], 0, v[20:21]
	v_lshl_add_u64 v[18:19], v[18:19], 0, v[136:137]
	v_lshlrev_b32_e32 v136, 2, v29
	v_lshl_add_u64 v[20:21], v[20:21], 0, v[136:137]
	v_add_u32_e32 v3, 0x600, v3
	v_lshlrev_b32_e32 v136, 1, v29
	s_waitcnt vmcnt(1)
	v_pk_add_f32 v[4:5], v[4:5], v[22:23]
	v_pk_add_f32 v[6:7], v[6:7], v[12:13]
	s_waitcnt vmcnt(0)
	v_pk_add_f32 v[8:9], v[8:9], v[24:25]
	v_pk_add_f32 v[10:11], v[10:11], v[14:15]
	v_cvt_pk_bf16_f32 v4, v4, v5
	v_cvt_pk_bf16_f32 v5, v6, v7
	v_cvt_pk_bf16_f32 v6, v8, v9
	v_cvt_pk_bf16_f32 v7, v10, v11
	global_store_dwordx4 v[18:19], v[4:7], off nt
	global_load_dwordx4 v[4:7], v[20:21], off nt
	s_nop 0
	global_load_dwordx4 v[8:11], v[20:21], off offset:16 nt
	v_ashrrev_i32_e32 v18, 5, v3
	v_lshl_or_b32 v3, v16, 9, v2
	ds_read_b128 v[12:15], v3
	v_xor_b32_e32 v20, v18, v142
	v_ashrrev_i32_e32 v19, 31, v18
	v_lshlrev_b32_e32 v3, 3, v20
	v_mad_i64_i32 v[16:17], s[24:25], v16, s21, v[26:27]
	s_waitcnt lgkmcnt(0)
	v_lshlrev_b32_e32 v22, 16, v12
	v_and_b32_e32 v23, 0xffff0000, v12
	v_lshlrev_b32_e32 v12, 16, v13
	v_and_b32_e32 v13, 0xffff0000, v13
	v_lshlrev_b32_e32 v24, 16, v14
	v_and_b32_e32 v25, 0xffff0000, v14
	v_lshlrev_b32_e32 v14, 16, v15
	v_and_b32_e32 v15, 0xffff0000, v15
	v_lshlrev_b64 v[20:21], 13, v[18:19]
	v_and_b32_e32 v3, 0xf8, v3
	v_lshl_add_u64 v[20:21], s[16:17], 0, v[20:21]
	v_lshl_add_u64 v[16:17], v[16:17], 0, v[136:137]
	v_lshlrev_b32_e32 v136, 2, v3
	v_lshl_add_u64 v[20:21], v[20:21], 0, v[136:137]
	v_lshlrev_b32_e32 v136, 1, v3
	s_waitcnt vmcnt(1)
	v_pk_add_f32 v[4:5], v[4:5], v[22:23]
	v_pk_add_f32 v[6:7], v[6:7], v[12:13]
	s_waitcnt vmcnt(0)
	v_pk_add_f32 v[8:9], v[8:9], v[24:25]
	v_pk_add_f32 v[10:11], v[10:11], v[14:15]
	v_cvt_pk_bf16_f32 v4, v4, v5
	v_cvt_pk_bf16_f32 v5, v6, v7
	v_cvt_pk_bf16_f32 v6, v8, v9
	v_cvt_pk_bf16_f32 v7, v10, v11
	global_store_dwordx4 v[16:17], v[4:7], off nt
	global_load_dwordx4 v[4:7], v[20:21], off nt
	s_nop 0
	global_load_dwordx4 v[8:11], v[20:21], off offset:16 nt
	v_lshl_or_b32 v12, v18, 9, v2
	ds_read_b128 v[12:15], v12
	v_mad_i64_i32 v[16:17], s[24:25], v18, s21, v[26:27]
	v_lshl_add_u64 v[16:17], v[16:17], 0, v[136:137]
	s_waitcnt lgkmcnt(0)
	v_lshlrev_b32_e32 v18, 16, v12
	v_and_b32_e32 v19, 0xffff0000, v12
	v_lshlrev_b32_e32 v12, 16, v13
	v_and_b32_e32 v13, 0xffff0000, v13
	v_lshlrev_b32_e32 v20, 16, v14
	v_and_b32_e32 v21, 0xffff0000, v14
	v_lshlrev_b32_e32 v14, 16, v15
	v_and_b32_e32 v15, 0xffff0000, v15
	s_waitcnt vmcnt(1)
	v_pk_add_f32 v[4:5], v[4:5], v[18:19]
	v_pk_add_f32 v[6:7], v[6:7], v[12:13]
	s_waitcnt vmcnt(0)
	v_pk_add_f32 v[8:9], v[8:9], v[20:21]
	v_pk_add_f32 v[10:11], v[10:11], v[14:15]
	v_cvt_pk_bf16_f32 v4, v4, v5
	v_cvt_pk_bf16_f32 v5, v6, v7
	v_cvt_pk_bf16_f32 v6, v8, v9
	v_cvt_pk_bf16_f32 v7, v10, v11
	global_store_dwordx4 v[16:17], v[4:7], off nt
	s_cbranch_scc1 .LBB0_1005
	s_add_i32 s23, s23, s33
	s_cmpk_gt_i32 s23, 0xff
	s_barrier
	s_cbranch_scc0 .LBB0_1002

; template <class Epi>
; DEV void gemm256_tile(const bf16_t* __restrict__ A, int lda, const bf16_t* __restrict__ Bt, int ldb, int K, unsigned char* lds, const Epi& epi) {
;     ...
; #pragma unroll 4
;         for (int i = 0; i < 16; ++i) {
;             const int idx = tid + 512 * i, row = idx >> 5, cp = idx & 31, c = cp ^ (row & 31);
;             const uint4 d = *(const uint4*)(lds + row * 512 + (cp << 4));
;             *(uint4*)(epi.obase + (size_t)row * epi.old + c * 8) = epi.finish(row, c * 8, d);
;         }
; __global__ void __launch_bounds__(512) hymba_fwd(Params p) {
;     ...
;             for (int t = bid; t < 32 * 8; t += ng) { int nt, mt; tile_map(t, 32, 8, mt, nt);
;                 EpiBfS e{qx + (size_t)mt * 256 * LDB + nt * 256, LDB};
;                 gemm256_tile(hbuf + (size_t)mt * 256 * LDB, LDB, Wt_cq + (size_t)nt * 256 * LDB, LDB, D, lds, e);
;             }
.LBB0_1238:
	v_add_u32_e32 v3, s12, v144
	v_ashrrev_i32_e32 v4, 5, v3
	v_add_u32_e32 v5, 0x200, v3
	v_add_u32_e32 v6, 0x400, v3
	v_add_u32_e32 v3, 0x600, v3
	v_xor_b32_e32 v7, v4, v144
	v_lshl_or_b32 v8, v4, 9, v2
	v_ashrrev_i32_e32 v9, 5, v5
	v_ashrrev_i32_e32 v10, 5, v6
	v_ashrrev_i32_e32 v3, 5, v3
	v_mad_i64_i32 v[20:21], s[20:21], v4, s16, v[26:27]
	v_lshlrev_b32_e32 v11, 4, v7
	ds_read_b128 v[4:7], v8
	v_xor_b32_e32 v8, v9, v144
	v_lshl_or_b32 v12, v9, 9, v2
	v_xor_b32_e32 v13, v10, v144
	v_lshl_or_b32 v14, v10, 9, v2
	v_xor_b32_e32 v15, v3, v144
	v_lshl_or_b32 v16, v3, 9, v2
	v_mad_i64_i32 v[22:23], s[20:21], v9, s16, v[26:27]
	v_mad_i64_i32 v[24:25], s[20:21], v10, s16, v[26:27]
	v_mad_i64_i32 v[28:29], s[20:21], v3, s16, v[26:27]
	v_and_b32_e32 v138, 0x1f0, v11
	v_lshlrev_b32_e32 v3, 4, v8
	ds_read_b128 v[8:11], v12
	v_lshlrev_b32_e32 v30, 4, v13
	v_lshlrev_b32_e32 v31, 4, v15
	ds_read_b128 v[12:15], v14
	ds_read_b128 v[16:19], v16
	v_lshl_add_u64 v[20:21], v[20:21], 0, v[138:139]
	v_and_b32_e32 v138, 0x1f0, v3
	s_addk_i32 s12, 0x800
	v_lshl_add_u64 v[22:23], v[22:23], 0, v[138:139]
	v_and_b32_e32 v138, 0x1f0, v30
	s_cmpk_lg_i32 s12, 0x2000
	v_lshl_add_u64 v[24:25], v[24:25], 0, v[138:139]
	v_and_b32_e32 v138, 0x1f0, v31
	s_waitcnt lgkmcnt(3)
	global_store_dwordx4 v[20:21], v[4:7], off nt
	s_nop 1
	v_lshl_add_u64 v[4:5], v[28:29], 0, v[138:139]
	s_waitcnt lgkmcnt(2)
	global_store_dwordx4 v[22:23], v[8:11], off nt
	s_waitcnt lgkmcnt(1)
	global_store_dwordx4 v[24:25], v[12:15], off nt
	s_waitcnt lgkmcnt(0)
	global_store_dwordx4 v[4:5], v[16:19], off nt
	s_cbranch_scc1 .LBB0_1238
	s_add_i32 s19, s19, s17
	s_cmpk_gt_i32 s19, 0xff
	s_waitcnt vmcnt(63) expcnt(7) lgkmcnt(15)
	s_barrier
	s_cbranch_scc0 .LBB0_1235

; DEV float bflo(unsigned u) { return __uint_as_float(u << 16); }
; DEV float bfhi(unsigned u) { return __uint_as_float(u & 0xffff0000u); }
; template <class Epi>
; DEV void gemm256_tile(const bf16_t* __restrict__ A, int lda, const bf16_t* __restrict__ Bt, int ldb, int K, unsigned char* lds, const Epi& epi) {
;     ...
; #pragma unroll 4
;         for (int i = 0; i < 16; ++i) {
;             const int idx = tid + 512 * i, row = idx >> 5, cp = idx & 31, c = cp ^ (row & 31);
;             const uint4 d = *(const uint4*)(lds + row * 512 + (cp << 4));
;             *(uint4*)(epi.obase + (size_t)row * epi.old + c * 8) = epi.finish(row, c * 8, d);
;         }
;     DEV uint4 finish(int r, int c, uint4 d) const {
;         const uint4 u = *(const uint4*)(res + (size_t)r * LDB + c);
;         const float r8[8] = {bflo(u.x), bfhi(u.x), bflo(u.y), bfhi(u.y), bflo(u.z), bfhi(u.z), bflo(u.w), bfhi(u.w)};
;         return add8_bf16(d, r8);
;     }
.LBB0_1468:
	v_add_u32_e32 v3, s12, v146
	v_ashrrev_i32_e32 v8, 5, v3
	v_xor_b32_e32 v6, v8, v146
	v_lshlrev_b32_e32 v6, 4, v6
	v_mad_i64_i32 v[4:5], s[20:21], v8, s17, v[26:27]
	v_and_b32_e32 v140, 0x1f0, v6
	v_lshl_add_u64 v[4:5], v[4:5], 0, v[140:141]
	global_load_dwordx4 v[4:7], v[4:5], off
	v_add_u32_e32 v9, 0x200, v3
	v_lshl_or_b32 v10, v8, 9, v2
	v_mad_i64_i32 v[12:13], s[20:21], v8, s17, v[28:29]
	v_ashrrev_i32_e32 v24, 5, v9
	ds_read_b128 v[8:11], v10
	v_xor_b32_e32 v16, v24, v146
	v_lshlrev_b32_e32 v16, 4, v16
	v_lshl_add_u64 v[12:13], v[12:13], 0, v[140:141]
	v_and_b32_e32 v140, 0x1f0, v16
	s_waitcnt lgkmcnt(0)
	v_lshlrev_b32_e32 v16, 16, v8
	v_and_b32_e32 v17, 0xffff0000, v8
	v_lshlrev_b32_e32 v8, 16, v9
	v_and_b32_e32 v9, 0xffff0000, v9
	v_lshlrev_b32_e32 v18, 16, v10
	v_and_b32_e32 v19, 0xffff0000, v10
	v_lshlrev_b32_e32 v10, 16, v11
	v_and_b32_e32 v11, 0xffff0000, v11
	v_mad_i64_i32 v[14:15], s[20:21], v24, s17, v[26:27]
	v_lshl_add_u64 v[14:15], v[14:15], 0, v[140:141]
	s_addk_i32 s12, 0x800
	s_cmpk_lg_i32 s12, 0x2000
	s_waitcnt vmcnt(0)
	v_lshlrev_b32_e32 v20, 16, v4
	v_and_b32_e32 v21, 0xffff0000, v4
	v_lshlrev_b32_e32 v4, 16, v5
	v_and_b32_e32 v5, 0xffff0000, v5
	v_lshlrev_b32_e32 v22, 16, v6
	v_and_b32_e32 v23, 0xffff0000, v6
	v_lshlrev_b32_e32 v6, 16, v7
	v_and_b32_e32 v7, 0xffff0000, v7
	v_pk_add_f32 v[16:17], v[16:17], v[20:21]
	v_pk_add_f32 v[8:9], v[8:9], v[4:5]
	v_pk_add_f32 v[18:19], v[18:19], v[22:23]
	v_pk_add_f32 v[10:11], v[10:11], v[6:7]
	v_cvt_pk_bf16_f32 v4, v16, v17
	v_cvt_pk_bf16_f32 v5, v8, v9
	v_cvt_pk_bf16_f32 v6, v18, v19
	v_cvt_pk_bf16_f32 v7, v10, v11
	global_store_dwordx4 v[12:13], v[4:7], off nt
	global_load_dwordx4 v[4:7], v[14:15], off
	v_add_u32_e32 v8, 0x400, v3
	v_ashrrev_i32_e32 v25, 5, v8
	v_lshl_or_b32 v8, v24, 9, v2
	ds_read_b128 v[8:11], v8
	v_xor_b32_e32 v16, v25, v146
	v_mad_i64_i32 v[12:13], s[20:21], v24, s17, v[28:29]
	v_lshlrev_b32_e32 v16, 4, v16
	v_lshl_add_u64 v[12:13], v[12:13], 0, v[140:141]
	v_and_b32_e32 v140, 0x1f0, v16
	s_waitcnt lgkmcnt(0)
	v_lshlrev_b32_e32 v16, 16, v8
	v_and_b32_e32 v17, 0xffff0000, v8
	v_lshlrev_b32_e32 v8, 16, v9
	v_and_b32_e32 v9, 0xffff0000, v9
	v_lshlrev_b32_e32 v18, 16, v10
	v_and_b32_e32 v19, 0xffff0000, v10
	v_lshlrev_b32_e32 v10, 16, v11
	v_and_b32_e32 v11, 0xffff0000, v11
	v_mad_i64_i32 v[14:15], s[20:21], v25, s17, v[26:27]
	v_lshl_add_u64 v[14:15], v[14:15], 0, v[140:141]
	v_add_u32_e32 v3, 0x600, v3
	v_ashrrev_i32_e32 v3, 5, v3
	s_waitcnt vmcnt(0)
	v_lshlrev_b32_e32 v20, 16, v4
	v_and_b32_e32 v21, 0xffff0000, v4
	v_lshlrev_b32_e32 v4, 16, v5
	v_and_b32_e32 v5, 0xffff0000, v5
	v_lshlrev_b32_e32 v22, 16, v6
	v_and_b32_e32 v23, 0xffff0000, v6
	v_lshlrev_b32_e32 v6, 16, v7
	v_and_b32_e32 v7, 0xffff0000, v7
	v_pk_add_f32 v[16:17], v[16:17], v[20:21]
	v_pk_add_f32 v[8:9], v[8:9], v[4:5]
	v_pk_add_f32 v[18:19], v[18:19], v[22:23]
	v_pk_add_f32 v[10:11], v[10:11], v[6:7]
	v_cvt_pk_bf16_f32 v4, v16, v17
	v_cvt_pk_bf16_f32 v5, v8, v9
	v_cvt_pk_bf16_f32 v6, v18, v19
	v_cvt_pk_bf16_f32 v7, v10, v11
	global_store_dwordx4 v[12:13], v[4:7], off nt
	global_load_dwordx4 v[4:7], v[14:15], off
	v_lshl_or_b32 v8, v25, 9, v2
	ds_read_b128 v[8:11], v8
	v_xor_b32_e32 v16, v3, v146
	v_mad_i64_i32 v[12:13], s[20:21], v25, s17, v[28:29]
	v_lshlrev_b32_e32 v16, 4, v16
	v_lshl_add_u64 v[12:13], v[12:13], 0, v[140:141]
	v_and_b32_e32 v140, 0x1f0, v16
	s_waitcnt lgkmcnt(0)
	v_lshlrev_b32_e32 v16, 16, v8
	v_and_b32_e32 v17, 0xffff0000, v8
	v_lshlrev_b32_e32 v8, 16, v9
	v_and_b32_e32 v9, 0xffff0000, v9
	v_lshlrev_b32_e32 v18, 16, v10
	v_and_b32_e32 v19, 0xffff0000, v10
	v_lshlrev_b32_e32 v10, 16, v11
	v_and_b32_e32 v11, 0xffff0000, v11
	v_mad_i64_i32 v[14:15], s[20:21], v3, s17, v[26:27]
	v_lshl_add_u64 v[14:15], v[14:15], 0, v[140:141]
	s_waitcnt vmcnt(0)
	v_lshlrev_b32_e32 v20, 16, v4
	v_and_b32_e32 v21, 0xffff0000, v4
	v_lshlrev_b32_e32 v4, 16, v5
	v_and_b32_e32 v5, 0xffff0000, v5
	v_lshlrev_b32_e32 v22, 16, v6
	v_and_b32_e32 v23, 0xffff0000, v6
	v_lshlrev_b32_e32 v6, 16, v7
	v_and_b32_e32 v7, 0xffff0000, v7
	v_pk_add_f32 v[16:17], v[16:17], v[20:21]
	v_pk_add_f32 v[8:9], v[8:9], v[4:5]
	v_pk_add_f32 v[18:19], v[18:19], v[22:23]
	v_pk_add_f32 v[10:11], v[10:11], v[6:7]
	v_cvt_pk_bf16_f32 v4, v16, v17
	v_cvt_pk_bf16_f32 v5, v8, v9
	v_cvt_pk_bf16_f32 v6, v18, v19
	v_cvt_pk_bf16_f32 v7, v10, v11
	global_store_dwordx4 v[12:13], v[4:7], off nt
	global_load_dwordx4 v[4:7], v[14:15], off
	v_lshl_or_b32 v8, v3, 9, v2
	ds_read_b128 v[8:11], v8
	v_mad_i64_i32 v[12:13], s[20:21], v3, s17, v[28:29]
	v_lshl_add_u64 v[12:13], v[12:13], 0, v[140:141]
	s_waitcnt lgkmcnt(0)
	v_lshlrev_b32_e32 v14, 16, v8
	v_and_b32_e32 v15, 0xffff0000, v8
	v_lshlrev_b32_e32 v8, 16, v9
	v_and_b32_e32 v9, 0xffff0000, v9
	v_lshlrev_b32_e32 v16, 16, v10
	v_and_b32_e32 v17, 0xffff0000, v10
	v_lshlrev_b32_e32 v10, 16, v11
	v_and_b32_e32 v11, 0xffff0000, v11
	s_waitcnt vmcnt(0)
	v_lshlrev_b32_e32 v18, 16, v4
	v_and_b32_e32 v19, 0xffff0000, v4
	v_lshlrev_b32_e32 v4, 16, v5
	v_and_b32_e32 v5, 0xffff0000, v5
	v_lshlrev_b32_e32 v20, 16, v6
	v_and_b32_e32 v21, 0xffff0000, v6
	v_lshlrev_b32_e32 v6, 16, v7
	v_and_b32_e32 v7, 0xffff0000, v7
	v_pk_add_f32 v[14:15], v[14:15], v[18:19]
	v_pk_add_f32 v[8:9], v[8:9], v[4:5]
	v_pk_add_f32 v[16:17], v[16:17], v[20:21]
	v_pk_add_f32 v[10:11], v[10:11], v[6:7]
	v_cvt_pk_bf16_f32 v4, v14, v15
	v_cvt_pk_bf16_f32 v5, v8, v9
	v_cvt_pk_bf16_f32 v6, v16, v17
	v_cvt_pk_bf16_f32 v7, v10, v11
	global_store_dwordx4 v[12:13], v[4:7], off nt
	s_cbranch_scc1 .LBB0_1468
	s_add_i32 s19, s19, s33
	s_cmpk_gt_i32 s19, 0xff
	s_barrier
	s_cbranch_scc0 .LBB0_1465
